# first grid barrier replaced by a wait on the 256 GEMV items that produce shift1/scale1 (P1 starts per block as soon as they are complete)
# baseline (speedup 1.0000x reference)
.LBB0_8:
	v_lshlrev_b64 v[2:3], 2, v[22:23]
	v_lshl_add_u64 v[4:5], s[50:51], 0, v[2:3]
	v_lshl_add_u64 v[2:3], s[0:1], 0, v[2:3]
	global_atomic_add_f32 v[4:5], v30, off
	global_atomic_add_f32 v[2:3], v26, off
	global_atomic_add_f32 v[4:5], v31, off offset:4
	global_atomic_add_f32 v[2:3], v27, off offset:4
	global_atomic_add_f32 v[4:5], v28, off offset:8
	global_atomic_add_f32 v[2:3], v24, off offset:8
	global_atomic_add_f32 v[4:5], v29, off offset:12
	global_atomic_add_f32 v[2:3], v25, off offset:12
	s_mul_hi_i32 s24, s28, 0x38e38e39
	s_lshr_b32 s25, s24, 31
	s_ashr_i32 s24, s24, 4
	s_add_i32 s24, s24, s25
	s_mul_i32 s25, s24, 0x48
	s_sub_i32 s25, s28, s25
	s_cmp_lt_u32 s25, 16
	s_cbranch_scc0 .Lmy_gv_nosig
	s_waitcnt vmcnt(0)
	s_mov_b64 s[24:25], exec
	s_mov_b64 exec, 1
	v_mov_b32_e32 v2, 0x33000
	v_mov_b32_e32 v3, 1
	global_atomic_add v2, v3, s[50:51]
	s_mov_b64 exec, s[24:25]
.Lmy_gv_nosig:
	s_add_i32 s28, s28, s72
	s_cmpk_lt_i32 s28, 0x480
	s_cbranch_scc0 .LBB0_13

.LBB0_139:
	v_readlane_b32 s0, v254, 0
	v_readlane_b32 s1, v254, 1
	s_cmp_gt_i32 s1, 1
	s_cselect_b64 s[0:1], -1, 0
	s_and_b64 s[4:5], s[4:5], s[0:1]
	s_andn2_b64 vcc, exec, s[4:5]
	s_cbranch_vccnz .LBB0_193
	s_waitcnt vmcnt(0)
	s_waitcnt lgkmcnt(0)
	s_barrier
	s_mov_b64 s[4:5], exec
	v_readlane_b32 s6, v254, 7
	v_readlane_b32 s7, v254, 8
	s_and_b64 s[6:7], s[4:5], s[6:7]
	s_mov_b64 exec, s[6:7]
	s_cbranch_execz .LBB0_192
	s_movk_i32 s6, 0x1000
.Lmy_s0_spin:
	v_mov_b32_e32 v2, 0x33000
	global_load_dword v3, v2, s[50:51] sc1
	s_waitcnt vmcnt(0)
	v_cmp_gt_u32_e32 vcc, 0x100, v3
	s_cbranch_vccz .Lmy_s0_go
	s_sleep 2
	s_sub_u32 s6, s6, 1
	s_cmp_lg_u32 s6, 0
	s_cbranch_scc1 .Lmy_s0_spin
.Lmy_s0_go:
	buffer_inv sc1
	s_waitcnt vmcnt(0)
	s_branch .LBB0_192
	s_add_i32 s6, 0, 0x23fc0
	v_mov_b32_e32 v2, s6
	s_waitcnt vmcnt(0) expcnt(0) lgkmcnt(0)
	ds_read_b32 v4, v2
	s_add_i32 s6, 0, 0x23fc4
	v_mov_b32_e32 v2, s6
	ds_read_b32 v2, v2
	s_waitcnt lgkmcnt(1)
	v_cmp_ne_u32_e32 vcc, 0, v4
	s_cbranch_vccnz .LBB0_156
	v_readlane_b32 s6, v254, 2
	v_readlane_b32 s7, v254, 3
	s_load_dwordx2 s[12:13], s[6:7], 0x4
	s_add_u32 s6, s50, 0x28200
	s_addc_u32 s7, s51, 0
	s_add_u32 s10, s50, 0x28400
	s_addc_u32 s11, s51, 0
	s_waitcnt lgkmcnt(0)
	s_mul_i32 s28, s12, s3
	s_add_u32 s12, s50, 0x28500
	s_mul_i32 s28, s28, s13
	s_addc_u32 s13, s51, 0
	s_add_u32 s14, s50, 0x28600
	s_addc_u32 s15, s51, 0
	s_add_u32 s18, s50, 0x28700
	s_addc_u32 s19, s51, 0
	s_add_u32 s20, s50, 0x28800
	s_addc_u32 s21, s51, 0
	s_add_u32 s24, s50, 0x28900
	s_addc_u32 s25, s51, 0
	s_add_u32 s26, s50, 0x28a00
	s_addc_u32 s27, s51, 0
	s_add_u32 s38, s50, 0x28b00
	s_addc_u32 s39, s51, 0
	s_add_u32 s42, s50, 0x28c00
	s_addc_u32 s43, s51, 0
	s_add_u32 s44, s50, 0x28d00
	s_addc_u32 s45, s51, 0
	s_add_u32 s56, s50, 0x28e00
	s_addc_u32 s57, s51, 0
	s_add_u32 s58, s50, 0x28f00
	s_addc_u32 s59, s51, 0
	s_add_u32 s60, s50, 0x29000
	s_addc_u32 s61, s51, 0
	s_add_u32 s62, s50, 0x29100
	s_addc_u32 s63, s51, 0
	s_add_u32 s74, s50, 0x29200
	s_addc_u32 s75, s51, 0
	s_add_u32 s76, s50, 0x29300
	s_addc_u32 s77, s51, 0
	s_mov_b32 s29, 1
	v_mov_b32_e32 v18, 0
	s_branch .LBB0_144
